# GU K-loop: first two ring waits of a tile's first iteration also count the 8 in-order epilogue stores (no wait for store acks)
# baseline (speedup 1.0000x reference)
.Lgu_pa_skip:
	v_lshl_add_u64 v[218:219], s[2:3], 0, v[144:145]
	s_add_i32 m0, s73, 0xc000
	ds_read_b128 v[174:177], v179
	ds_read_b128 v[180:183], v179 offset:1024
	ds_read_b128 v[184:187], v179 offset:2048
	ds_read_b128 v[188:191], v179 offset:3072
	ds_read_b128 v[214:217], v179 offset:4096
	ds_read_b128 v[228:231], v179 offset:5120
	ds_read_b128 v[232:235], v179 offset:6144
	ds_read_b128 v[236:239], v179 offset:7168
	global_load_lds_dwordx4 v[218:219], off
	v_lshl_add_u64 v[218:219], s[2:3], 0, v[142:143]
	s_add_i32 m0, s73, 0xe000
	s_nop 0
	global_load_lds_dwordx4 v[218:219], off
	s_cmp_eq_u32 s83, -2
	s_cbranch_scc0 .Lgu_w1n
	s_cmp_eq_u32 s81, 1
	s_cbranch_scc1 .Lgu_w1n
	s_waitcnt vmcnt(16)
	s_branch .Lgu_w1d
.Lgu_w1n:
	s_waitcnt vmcnt(8)
.Lgu_w1d:
	s_waitcnt lgkmcnt(0)
	s_barrier
	s_setprio 1
	s_waitcnt lgkmcnt(0)
	v_mfma_f32_16x16x32_bf16 v[122:125], v[130:133], v[174:177], v[122:125]
	v_mfma_f32_16x16x32_bf16 v[114:117], v[150:153], v[174:177], v[114:117]
	v_mfma_f32_16x16x32_bf16 v[106:109], v[130:133], v[184:187], v[106:109]
	v_mfma_f32_16x16x32_bf16 v[98:101], v[150:153], v[184:187], v[98:101]
	v_mfma_f32_16x16x32_bf16 v[90:93], v[130:133], v[214:217], v[90:93]
	v_mfma_f32_16x16x32_bf16 v[82:85], v[150:153], v[214:217], v[82:85]
	v_mfma_f32_16x16x32_bf16 v[74:77], v[130:133], v[232:235], v[74:77]
	v_mfma_f32_16x16x32_bf16 v[66:69], v[150:153], v[232:235], v[66:69]
	v_mfma_f32_16x16x32_bf16 v[122:125], v[146:149], v[180:183], v[122:125]
	v_mfma_f32_16x16x32_bf16 v[114:117], v[154:157], v[180:183], v[114:117]
	v_mfma_f32_16x16x32_bf16 v[106:109], v[146:149], v[188:191], v[106:109]
	v_mfma_f32_16x16x32_bf16 v[98:101], v[154:157], v[188:191], v[98:101]
	v_mfma_f32_16x16x32_bf16 v[90:93], v[146:149], v[228:231], v[90:93]
	v_mfma_f32_16x16x32_bf16 v[82:85], v[154:157], v[228:231], v[82:85]
	v_mfma_f32_16x16x32_bf16 v[74:77], v[146:149], v[236:239], v[74:77]
	v_mfma_f32_16x16x32_bf16 v[66:69], v[154:157], v[236:239], v[66:69]
	s_setprio 0
	s_setprio 1
	v_mfma_f32_16x16x32_bf16 v[126:129], v[158:161], v[174:177], v[126:129]
	v_mfma_f32_16x16x32_bf16 v[118:121], v[166:169], v[174:177], v[118:121]
	v_mfma_f32_16x16x32_bf16 v[110:113], v[158:161], v[184:187], v[110:113]
	v_mfma_f32_16x16x32_bf16 v[102:105], v[166:169], v[184:187], v[102:105]
	v_mfma_f32_16x16x32_bf16 v[94:97], v[158:161], v[214:217], v[94:97]
	v_mfma_f32_16x16x32_bf16 v[86:89], v[166:169], v[214:217], v[86:89]
	v_mfma_f32_16x16x32_bf16 v[78:81], v[158:161], v[232:235], v[78:81]
	v_mfma_f32_16x16x32_bf16 v[70:73], v[166:169], v[232:235], v[70:73]
	v_mfma_f32_16x16x32_bf16 v[126:129], v[162:165], v[180:183], v[126:129]
	v_mfma_f32_16x16x32_bf16 v[118:121], v[170:173], v[180:183], v[118:121]
	v_mfma_f32_16x16x32_bf16 v[110:113], v[162:165], v[188:191], v[110:113]
	v_mfma_f32_16x16x32_bf16 v[102:105], v[170:173], v[188:191], v[102:105]
	v_mfma_f32_16x16x32_bf16 v[94:97], v[162:165], v[228:231], v[94:97]
	v_mfma_f32_16x16x32_bf16 v[86:89], v[170:173], v[228:231], v[86:89]
	v_mfma_f32_16x16x32_bf16 v[78:81], v[162:165], v[236:239], v[78:81]
	v_mfma_f32_16x16x32_bf16 v[70:73], v[170:173], v[236:239], v[70:73]
	s_setprio 0
	s_barrier
	s_add_i32 s30, s30, s72
	v_lshl_add_u64 v[218:219], s[24:25], 0, v[138:139]
	s_mov_b32 m0, s30
	ds_read_b128 v[174:177], v179 offset:16384
	ds_read_b128 v[180:183], v179 offset:17408
	ds_read_b128 v[184:187], v179 offset:18432
	ds_read_b128 v[188:191], v179 offset:19456
	ds_read_b128 v[214:217], v179 offset:20480
	ds_read_b128 v[228:231], v179 offset:21504
	ds_read_b128 v[232:235], v179 offset:22528
	ds_read_b128 v[236:239], v179 offset:23552
	global_load_lds_dwordx4 v[218:219], off
	s_add_i32 m0, s30, 0x2000
	s_add_u32 s64, s24, 0x40000
	v_lshl_add_u64 v[240:241], s[24:25], 0, v[134:135]
	s_addc_u32 s65, s25, 0
	s_add_i32 s0, s0, s72
	global_load_lds_dwordx4 v[240:241], off
	v_lshl_add_u64 v[242:243], s[64:65], 0, v[138:139]
	s_mov_b32 m0, s0
	v_lshl_add_u64 v[244:245], s[42:43], 0, v[136:137]
	global_load_lds_dwordx4 v[242:243], off
	v_lshl_add_u64 v[242:243], s[64:65], 0, v[134:135]
	s_add_i32 m0, s0, 0x2000
	s_nop 0
	global_load_lds_dwordx4 v[242:243], off
	v_lshl_add_u64 v[242:243], s[42:43], 0, v[140:141]
	s_mov_b32 m0, s73
	s_nop 0
	global_load_lds_dwordx4 v[242:243], off
	s_mov_b32 m0, s74
	s_nop 0
	global_load_lds_dwordx4 v[244:245], off
	s_cmp_eq_u32 s83, -2
	s_cbranch_scc0 .Lgu_w2n
	s_cmp_eq_u32 s81, 1
	s_cbranch_scc1 .Lgu_w2n
	s_waitcnt vmcnt(16)
	s_branch .Lgu_w2d

.Lgu_w2d:
	s_waitcnt lgkmcnt(0)
	s_barrier
	s_setprio 1
	s_waitcnt lgkmcnt(0)
	v_mfma_f32_16x16x32_bf16 v[58:61], v[130:133], v[174:177], v[58:61]
	v_mfma_f32_16x16x32_bf16 v[50:53], v[150:153], v[174:177], v[50:53]
	v_mfma_f32_16x16x32_bf16 v[42:45], v[130:133], v[184:187], v[42:45]
	v_mfma_f32_16x16x32_bf16 v[34:37], v[150:153], v[184:187], v[34:37]
	v_mfma_f32_16x16x32_bf16 v[26:29], v[130:133], v[214:217], v[26:29]
	v_mfma_f32_16x16x32_bf16 v[18:21], v[150:153], v[214:217], v[18:21]
	v_mfma_f32_16x16x32_bf16 v[10:13], v[130:133], v[232:235], v[10:13]
	v_mfma_f32_16x16x32_bf16 v[6:9], v[150:153], v[232:235], v[6:9]
	v_mfma_f32_16x16x32_bf16 v[58:61], v[146:149], v[180:183], v[58:61]
	v_mfma_f32_16x16x32_bf16 v[50:53], v[154:157], v[180:183], v[50:53]
	v_mfma_f32_16x16x32_bf16 v[42:45], v[146:149], v[188:191], v[42:45]
	v_mfma_f32_16x16x32_bf16 v[34:37], v[154:157], v[188:191], v[34:37]
	v_mfma_f32_16x16x32_bf16 v[26:29], v[146:149], v[228:231], v[26:29]
	v_mfma_f32_16x16x32_bf16 v[18:21], v[154:157], v[228:231], v[18:21]
	v_mfma_f32_16x16x32_bf16 v[10:13], v[146:149], v[236:239], v[10:13]
	v_mfma_f32_16x16x32_bf16 v[6:9], v[154:157], v[236:239], v[6:9]
	s_setprio 0
	s_setprio 1
	v_mfma_f32_16x16x32_bf16 v[62:65], v[158:161], v[174:177], v[62:65]
	v_mfma_f32_16x16x32_bf16 v[54:57], v[166:169], v[174:177], v[54:57]
	v_mfma_f32_16x16x32_bf16 v[46:49], v[158:161], v[184:187], v[46:49]
	v_mfma_f32_16x16x32_bf16 v[38:41], v[166:169], v[184:187], v[38:41]
	v_mfma_f32_16x16x32_bf16 v[30:33], v[158:161], v[214:217], v[30:33]
	v_mfma_f32_16x16x32_bf16 v[22:25], v[166:169], v[214:217], v[22:25]
	v_mfma_f32_16x16x32_bf16 v[14:17], v[158:161], v[232:235], v[14:17]
	v_mfma_f32_16x16x32_bf16 v[2:5], v[166:169], v[232:235], v[2:5]
	v_mfma_f32_16x16x32_bf16 v[62:65], v[162:165], v[180:183], v[62:65]
	v_mfma_f32_16x16x32_bf16 v[54:57], v[170:173], v[180:183], v[54:57]
	v_mfma_f32_16x16x32_bf16 v[46:49], v[162:165], v[188:191], v[46:49]
	v_mfma_f32_16x16x32_bf16 v[38:41], v[170:173], v[188:191], v[38:41]
	v_mfma_f32_16x16x32_bf16 v[30:33], v[162:165], v[228:231], v[30:33]
	v_mfma_f32_16x16x32_bf16 v[22:25], v[170:173], v[228:231], v[22:25]
	v_mfma_f32_16x16x32_bf16 v[14:17], v[162:165], v[236:239], v[14:17]
	v_mfma_f32_16x16x32_bf16 v[2:5], v[170:173], v[236:239], v[2:5]
	s_setprio 0
	s_barrier
	s_add_i32 s0, 0, 0x18000
	v_add_u32_e32 v0, s0, v178
	s_add_i32 s30, 0, 0x1c000
	ds_read_b128 v[130:133], v0
	ds_read_b128 v[146:149], v0 offset:1024
	ds_read_b128 v[150:153], v0 offset:2048
	ds_read_b128 v[154:157], v0 offset:3072
	v_add_u32_e32 v0, s30, v178
	ds_read_b128 v[158:161], v0
	ds_read_b128 v[162:165], v0 offset:1024
	ds_read_b128 v[166:169], v0 offset:2048
	ds_read_b128 v[170:173], v0 offset:3072
	s_add_u32 s42, s42, 0x40000
	s_addc_u32 s43, s43, 0
	s_mov_b32 m0, s75
	v_lshl_add_u64 v[246:247], s[42:43], 0, v[140:141]
	ds_read_b128 v[174:177], v179 offset:32768
	ds_read_b128 v[180:183], v179 offset:33792
	ds_read_b128 v[184:187], v179 offset:34816
	ds_read_b128 v[188:191], v179 offset:35840
	ds_read_b128 v[214:217], v179 offset:36864
	ds_read_b128 v[228:231], v179 offset:37888
	ds_read_b128 v[232:235], v179 offset:38912
	ds_read_b128 v[236:239], v179 offset:39936
	s_cmp_eq_u32 s83, 12
	s_cbranch_scc0 .Lgu_pb_skip
	v_add_f32_e32 v221, v195, v194
	v_add_f32_e32 v253, v196, v197
	v_add_f32_e32 v221, v221, v253
	v_add_f32_e32 v222, v199, v198
	v_add_f32_e32 v253, v200, v201
	v_add_f32_e32 v222, v222, v253
	v_add_f32_e32 v223, v203, v202
	v_add_f32_e32 v253, v204, v205
	v_add_f32_e32 v223, v223, v253
	v_add_f32_e32 v224, v207, v206
	v_add_f32_e32 v253, v208, v209
	v_add_f32_e32 v224, v224, v253
	v_add_u32_e32 v253, 0x2000, v252
	global_load_dwordx4 v[194:197], v253, s[10:11]
	global_load_dwordx4 v[198:201], v253, s[10:11] offset:1024
	global_load_dwordx4 v[202:205], v253, s[10:11] offset:2048
	global_load_dwordx4 v[206:209], v253, s[10:11] offset:3072
